# speedup vs baseline: 1.0550x; 1.0251x over previous
; __device__ __forceinline__ void prep_phase(const Params& p, float* tile) {
;     ...
;       int kg = tid >> 7, col = tid & 127, n = nc * 128 + col;
;       const float* w = p.ada_w + ((size_t)li * D + kg * 256) * MODW + n;
;       const float* sk = sl + kg * 256;
;       float a0 = 0, a1 = 0, a2 = 0, a3 = 0, a4 = 0, a5 = 0, a6 = 0, a7 = 0, a8 = 0;
; #pragma unroll 8
;       for (int k = 0; k < 256; k++) {
;         float wv = w[(size_t)k * MODW];
;         a0 += sk[k] * wv; a1 += sk[1024 + k] * wv; a2 += sk[2048 + k] * wv; a3 += sk[3072 + k] * wv;
;         a4 += sk[4096 + k] * wv; a5 += sk[5120 + k] * wv; a6 += sk[6144 + k] * wv; a7 += sk[7168 + k] * wv;
;         a8 += sk[8192 + k] * wv;
;       }
.LBB0_54:
	v_lshl_add_u64 v[50:51], v[40:41], 0, s[14:15]
	global_load_dword v128, v[50:51], off
	v_add_co_u32_e32 v114, vcc, 0x9000, v50
	s_nop 1
	v_addc_co_u32_e32 v115, vcc, 0, v51, vcc
	global_load_dword v129, v[114:115], off
	v_add_co_u32_e32 v116, vcc, 0x12000, v50
	s_nop 1
	v_addc_co_u32_e32 v117, vcc, 0, v51, vcc
	global_load_dword v130, v[116:117], off
	v_add_co_u32_e32 v118, vcc, 0x1b000, v50
	s_nop 1
	v_addc_co_u32_e32 v119, vcc, 0, v51, vcc
	global_load_dword v131, v[118:119], off
	v_add_co_u32_e32 v120, vcc, 0x24000, v50
	s_nop 1
	v_addc_co_u32_e32 v121, vcc, 0, v51, vcc
	global_load_dword v132, v[120:121], off
	v_add_co_u32_e32 v122, vcc, 0x2d000, v50
	s_nop 1
	v_addc_co_u32_e32 v123, vcc, 0, v51, vcc
	global_load_dword v133, v[122:123], off
	v_add_co_u32_e32 v124, vcc, 0x36000, v50
	s_nop 1
	v_addc_co_u32_e32 v125, vcc, 0, v51, vcc
	global_load_dword v134, v[124:125], off
	v_add_co_u32_e32 v126, vcc, 0x3f000, v50
	s_nop 1
	v_addc_co_u32_e32 v127, vcc, 0, v51, vcc
	global_load_dword v135, v[126:127], off
	ds_read_b128 v[72:75], v70
	ds_read_b128 v[0:3], v70 offset:16
	ds_read_b128 v[76:79], v70 offset:4096
	s_mov_b32 s20, 0x12000
	s_add_u32 s14, s14, 0x48000
	s_waitcnt lgkmcnt(2)
	v_mov_b32_e32 v80, v72
	s_addc_u32 s15, s15, 0
	s_waitcnt lgkmcnt(0)
	v_mov_b32_e32 v81, v76
	v_mov_b32_e32 v76, v73
	s_cmp_eq_u32 s14, 0x900000
	s_waitcnt vmcnt(7)
	v_mov_b32_e32 v4, v128
	v_pk_fma_f32 v[104:105], v[4:5], v[80:81], v[48:49] op_sel_hi:[0,1,1]
	ds_read_b128 v[80:83], v70 offset:8192
	ds_read_b128 v[84:87], v70 offset:12288
	s_waitcnt lgkmcnt(1)
	v_mov_b32_e32 v48, v80
	s_waitcnt lgkmcnt(0)
	v_mov_b32_e32 v49, v84
	v_pk_fma_f32 v[106:107], v[4:5], v[48:49], v[46:47] op_sel_hi:[0,1,1]
	ds_read_b128 v[46:49], v70 offset:16384
	ds_read_b128 v[88:91], v70 offset:20480
	ds_read_b128 v[92:95], v70 offset:24576
	ds_read_b128 v[96:99], v70 offset:28672
	v_mov_b32_e32 v84, v81
	s_waitcnt lgkmcnt(3)
	v_mov_b32_e32 v108, v46
	s_waitcnt lgkmcnt(1)
	v_mov_b32_e32 v101, v92
	s_waitcnt lgkmcnt(0)
	v_mov_b32_e32 v100, v96
	v_pk_fma_f32 v[44:45], v[4:5], v[100:101], v[44:45] op_sel_hi:[0,1,1]
	ds_read_b128 v[100:103], v70 offset:32768
	v_fmac_f32_e32 v39, v4, v88
	v_mov_b32_e32 v92, v97
	s_waitcnt lgkmcnt(0)
	v_mov_b32_e32 v109, v100
	v_pk_fma_f32 v[42:43], v[4:5], v[108:109], v[42:43] op_sel_hi:[0,1,1]
	v_add_co_u32_e32 v108, vcc, s17, v50
	v_mov_b32_e32 v100, v47
	s_nop 0
	v_addc_co_u32_e32 v109, vcc, 0, v51, vcc
	v_add_co_u32_e32 v46, vcc, s20, v50
	s_mov_b32 s20, 0x1b000
	s_nop 0
	v_addc_co_u32_e32 v47, vcc, 0, v51, vcc
	s_waitcnt vmcnt(6)
	v_mov_b32_e32 v4, v129
	v_pk_fma_f32 v[72:73], v[4:5], v[76:77], v[104:105] op_sel_hi:[0,1,1]
	v_pk_fma_f32 v[76:77], v[4:5], v[84:85], v[106:107] op_sel_hi:[0,1,1]
	v_fmac_f32_e32 v39, v4, v89
	v_pk_fma_f32 v[44:45], v[4:5], v[92:93], v[44:45] op_sel_hi:[0,1,1]
	v_pk_fma_f32 v[42:43], v[4:5], v[100:101], v[42:43] op_sel_hi:[0,1,1]
	v_mov_b32_e32 v46, v74
	v_mov_b32_e32 v47, v78
	v_mov_b32_e32 v78, v75
	s_waitcnt vmcnt(5)
	v_mov_b32_e32 v4, v130
	v_pk_fma_f32 v[46:47], v[4:5], v[46:47], v[72:73] op_sel_hi:[0,1,1]
	v_mov_b32_e32 v72, v82
	v_mov_b32_e32 v73, v86
	v_pk_fma_f32 v[72:73], v[4:5], v[72:73], v[76:77] op_sel_hi:[0,1,1]
	v_mov_b32_e32 v76, v98
	v_mov_b32_e32 v77, v94
	v_pk_fma_f32 v[44:45], v[4:5], v[76:77], v[44:45] op_sel_hi:[0,1,1]
	v_mov_b32_e32 v76, v48
	v_mov_b32_e32 v77, v102
	v_pk_fma_f32 v[42:43], v[4:5], v[76:77], v[42:43] op_sel_hi:[0,1,1]
	v_add_co_u32_e32 v76, vcc, s20, v50
	v_fmac_f32_e32 v39, v4, v90
	s_nop 0
	v_addc_co_u32_e32 v77, vcc, 0, v51, vcc
	s_mov_b32 s20, 0x24000
	v_add_co_u32_e32 v48, vcc, s20, v50
	v_mov_b32_e32 v86, v83
	v_mov_b32_e32 v94, v99
	v_mov_b32_e32 v102, v49
	v_addc_co_u32_e32 v49, vcc, 0, v51, vcc
	s_mov_b32 s20, 0x2d000
	s_waitcnt vmcnt(4)
	v_mov_b32_e32 v4, v131
	v_pk_fma_f32 v[76:77], v[4:5], v[78:79], v[46:47] op_sel_hi:[0,1,1]
	v_pk_fma_f32 v[46:47], v[4:5], v[86:87], v[72:73] op_sel_hi:[0,1,1]
	v_fmac_f32_e32 v39, v4, v91
	v_pk_fma_f32 v[44:45], v[4:5], v[94:95], v[44:45] op_sel_hi:[0,1,1]
	v_pk_fma_f32 v[42:43], v[4:5], v[102:103], v[42:43] op_sel_hi:[0,1,1]
	ds_read_b128 v[72:75], v70 offset:4112
	v_mov_b32_e32 v48, v0
	s_waitcnt lgkmcnt(0)
	v_mov_b32_e32 v49, v72
	v_mov_b32_e32 v72, v1
	s_waitcnt vmcnt(3)
	v_mov_b32_e32 v4, v132
	v_pk_fma_f32 v[48:49], v[4:5], v[48:49], v[76:77] op_sel_hi:[0,1,1]
	ds_read_b128 v[76:79], v70 offset:8208
	ds_read_b128 v[80:83], v70 offset:12304
	s_waitcnt lgkmcnt(1)
	v_mov_b32_e32 v84, v76
	s_waitcnt lgkmcnt(0)
	v_mov_b32_e32 v85, v80
	v_pk_fma_f32 v[46:47], v[4:5], v[84:85], v[46:47] op_sel_hi:[0,1,1]
	ds_read_b128 v[84:87], v70 offset:16400
	ds_read_b128 v[88:91], v70 offset:20496
	ds_read_b128 v[92:95], v70 offset:24592
	ds_read_b128 v[96:99], v70 offset:28688
	v_mov_b32_e32 v80, v77
	s_waitcnt lgkmcnt(3)
	v_mov_b32_e32 v104, v84
	s_waitcnt lgkmcnt(1)
	v_mov_b32_e32 v101, v92
	s_waitcnt lgkmcnt(0)
	v_mov_b32_e32 v100, v96
	v_pk_fma_f32 v[44:45], v[4:5], v[100:101], v[44:45] op_sel_hi:[0,1,1]
	ds_read_b128 v[100:103], v70 offset:32784
	v_fmac_f32_e32 v39, v4, v88
	v_mov_b32_e32 v92, v97
	v_add_u32_e32 v70, 32, v70
	s_waitcnt lgkmcnt(0)
	v_mov_b32_e32 v105, v100
	v_pk_fma_f32 v[42:43], v[4:5], v[104:105], v[42:43] op_sel_hi:[0,1,1]
	v_add_co_u32_e32 v104, vcc, s20, v50
	v_mov_b32_e32 v100, v85
	s_nop 0
	v_addc_co_u32_e32 v105, vcc, 0, v51, vcc
	s_mov_b32 s20, 0x36000
	s_waitcnt vmcnt(2)
	v_mov_b32_e32 v0, v133
	v_pk_fma_f32 v[48:49], v[0:1], v[72:73], v[48:49] op_sel_hi:[0,1,1]
	v_pk_fma_f32 v[46:47], v[0:1], v[80:81], v[46:47] op_sel_hi:[0,1,1]
	v_fmac_f32_e32 v39, v0, v89
	v_pk_fma_f32 v[44:45], v[0:1], v[92:93], v[44:45] op_sel_hi:[0,1,1]
	v_pk_fma_f32 v[0:1], v[0:1], v[100:101], v[42:43] op_sel_hi:[0,1,1]
	v_add_co_u32_e32 v42, vcc, s20, v50
	s_mov_b32 s20, 0x3f000
	s_nop 0
	v_addc_co_u32_e32 v43, vcc, 0, v51, vcc
	v_mov_b32_e32 v42, v2
	v_mov_b32_e32 v43, v74
	v_mov_b32_e32 v74, v3
	s_waitcnt vmcnt(1)
	v_mov_b32_e32 v4, v134
	v_pk_fma_f32 v[42:43], v[4:5], v[42:43], v[48:49] op_sel_hi:[0,1,1]
	v_mov_b32_e32 v48, v78
	v_mov_b32_e32 v49, v82
	v_pk_fma_f32 v[46:47], v[4:5], v[48:49], v[46:47] op_sel_hi:[0,1,1]
	v_mov_b32_e32 v48, v98
	v_mov_b32_e32 v49, v94
	v_pk_fma_f32 v[44:45], v[4:5], v[48:49], v[44:45] op_sel_hi:[0,1,1]
	v_mov_b32_e32 v48, v86
	v_mov_b32_e32 v49, v102
	v_pk_fma_f32 v[0:1], v[4:5], v[48:49], v[0:1] op_sel_hi:[0,1,1]
	v_add_co_u32_e32 v48, vcc, s20, v50
	v_fmac_f32_e32 v39, v4, v90
	s_nop 0
	v_addc_co_u32_e32 v49, vcc, 0, v51, vcc
	v_mov_b32_e32 v82, v79
	v_mov_b32_e32 v94, v99
	v_mov_b32_e32 v102, v87
	s_waitcnt vmcnt(0)
	v_mov_b32_e32 v2, v135
	v_pk_fma_f32 v[48:49], v[2:3], v[74:75], v[42:43] op_sel_hi:[0,1,1]
	v_pk_fma_f32 v[46:47], v[2:3], v[82:83], v[46:47] op_sel_hi:[0,1,1]
	v_fmac_f32_e32 v39, v2, v91
	v_pk_fma_f32 v[44:45], v[2:3], v[94:95], v[44:45] op_sel_hi:[0,1,1]
	v_pk_fma_f32 v[42:43], v[2:3], v[102:103], v[0:1] op_sel_hi:[0,1,1]
	s_cbranch_scc0 .LBB0_54
; __device__ __forceinline__ void prep_phase(const Params& p, float* tile) {
;     ...
;       float* rr = red + (kg * 9) * 128 + col;
;       rr[0] = a0; rr[128] = a1; rr[256] = a2; rr[384] = a3; rr[512] = a4; rr[640] = a5; rr[768] = a6; rr[896] = a7; rr[1024] = a8;
;       __syncthreads();
;       for (int e = tid; e < 9 * 128; e += 512) {
;         int r = e >> 7, c2 = e & 127;
;         float v = p.ada_b[li * MODW + nc * 128 + c2] + red[(0 * 9 + r) * 128 + c2] + red[(1 * 9 + r) * 128 + c2] +
;                   red[(2 * 9 + r) * 128 + c2] + red[(3 * 9 + r) * 128 + c2];
;         p.mod[(size_t)(li * 9 + r) * MODW + nc * 128 + c2] = v;
	ds_write2st64_b32 v13, v48, v49 offset0:144 offset1:146
	ds_write2st64_b32 v13, v46, v47 offset0:148 offset1:150
	ds_write2st64_b32 v13, v42, v39 offset0:152 offset1:154
	ds_write2st64_b32 v13, v45, v44 offset0:156 offset1:158
	ds_write_b32 v13, v43 offset:40960
	s_waitcnt lgkmcnt(0)
	s_barrier
	s_and_saveexec_b64 s[14:15], s[4:5]
	s_load_dwordx16 s[40:55], s[0:1], 0x0
	s_cbranch_execz .LBB0_58
	s_mul_i32 s30, s18, 0x2400
	s_add_i32 s30, s30, s19
	s_mul_i32 s31, s18, 9
	s_lshl_b32 s18, s19, 2
	s_add_u32 s18, s76, s18
	s_addc_u32 s19, s77, 0
	s_mov_b64 s[20:21], 0
	v_mov_b32_e32 v0, v69
	v_mov_b32_e32 v1, v6
